# v36 + attention unit-top workgroup barrier removed: units alternate the starting LDS buffer so a new unit's first tile never lands in the buffer the previous unit's last step reads
# speedup vs baseline: 1.0058x; 1.0058x over previous
.LBB0_790:
	v_readfirstlane_b32 s100, v235
	s_nop 3
	s_mul_i32 s101, s100, s42
	s_sub_i32 s0, s42, 1
	s_sub_i32 s0, s0, s2
	s_bitcmp0_b32 s100, 0
	s_cselect_b32 s0, s2, s0
	s_add_i32 s101, s101, s0
	v_add_u32_e32 v235, 1, v235
	v_mov_b32_e32 v0, s101
	s_movk_i32 s0, 0x480
	s_mov_b64 s[8:9], -1
	v_cmp_gt_i32_e64 s[6:7], s0, v0
	s_and_saveexec_b64 s[68:69], s[6:7]
	s_cbranch_execz .LBB0_789
	v_ashrrev_i32_e32 v1, 31, v0
	v_lshrrev_b32_e32 v1, 25, v1
	v_add_u32_e32 v1, v0, v1
	v_ashrrev_i32_e32 v8, 7, v1
	v_and_b32_e32 v1, 0xffffff80, v1
	v_sub_u32_e32 v0, v0, v1
	v_mov_b32_e32 v1, 11
	v_lshrrev_b16_sdwa v1, v1, sext(v0) dst_sel:DWORD dst_unused:UNUSED_PAD src0_sel:DWORD src1_sel:BYTE_0
	v_and_b32_e32 v1, 15, v1
	v_add_u16_e32 v1, v0, v1
	v_sub_u32_e32 v9, 8, v8
	v_ashrrev_i16_sdwa v2, v198, sext(v1) dst_sel:DWORD dst_unused:UNUSED_PAD src0_sel:DWORD src1_sel:BYTE_0
	s_movk_i32 s0, 0x810
	v_and_b32_e32 v1, 0xf0, v1
	v_mul_hi_i32_i24_sdwa v135, sext(v2), s0 dst_sel:DWORD dst_unused:UNUSED_PAD src0_sel:WORD_0 src1_sel:DWORD
	v_mul_i32_i24_sdwa v134, sext(v2), s0 dst_sel:DWORD dst_unused:UNUSED_PAD src0_sel:WORD_0 src1_sel:DWORD
	v_mul_hi_i32_i24_e32 v3, 0x2040, v0
	v_mul_i32_i24_e32 v2, 0x2040, v0
	v_lshlrev_b32_e32 v10, 8, v9
	v_sub_u16_e32 v4, v0, v1
	v_lshl_add_u64 v[140:141], s[62:63], 0, v[2:3]
	v_add_u32_e32 v164, v10, v156
	v_mov_b32_e32 v2, 6
	v_lshlrev_b32_sdwa v138, v2, sext(v4) dst_sel:DWORD dst_unused:UNUSED_PAD src0_sel:DWORD src1_sel:BYTE_0
	v_max_i32_e32 v6, 0xf0, v164
	v_ashrrev_i32_e32 v139, 31, v138
	v_add_u32_e32 v172, 0xffffff10, v6
	v_lshlrev_b64 v[2:3], 1, v[138:139]
	v_lshl_add_u64 v[6:7], v[134:135], 0, v[172:173]
	v_lshl_add_u64 v[4:5], v[120:121], 0, v[2:3]
	v_lshlrev_b64 v[6:7], 12, v[6:7]
	v_lshl_add_u64 v[6:7], v[4:5], 0, v[6:7]
	v_or_b32_e32 v139, 16, v164
	global_load_dwordx4 v[20:23], v[6:7], off
	global_load_dwordx4 v[24:27], v[6:7], off offset:64
	v_max_i32_e32 v6, 0xf0, v139
	v_add_u32_e32 v172, 0xffffff10, v6
	v_lshl_add_u64 v[6:7], v[134:135], 0, v[172:173]
	v_lshlrev_b64 v[6:7], 12, v[6:7]
	v_ashrrev_i32_e32 v1, 31, v0
	v_lshl_add_u64 v[4:5], v[4:5], 0, v[6:7]
	global_load_dwordx4 v[28:31], v[4:5], off
	global_load_dwordx4 v[32:35], v[4:5], off offset:64
	v_lshl_add_u64 v[4:5], v[134:135], 0, v[124:125]
	v_lshlrev_b64 v[0:1], 6, v[0:1]
	v_lshlrev_b64 v[4:5], 11, v[4:5]
	v_lshl_add_u64 v[0:1], v[0:1], 0, v[122:123]
	v_mov_b64_e32 v[6:7], s[88:89]
	v_lshl_add_u64 v[4:5], s[70:71], 0, v[4:5]
	v_mad_u64_u32 v[144:145], s[6:7], v0, s52, v[6:7]
	v_lshl_add_u64 v[4:5], v[4:5], 0, v[2:3]
	v_lshlrev_b32_e32 v142, 1, v126
	v_mov_b32_e32 v143, v173
	v_mad_i32_i24 v145, v1, s52, v145
	v_mov_b32_e32 v131, v173
	v_lshlrev_b32_e32 v165, 2, v9
	v_lshl_add_u64 v[4:5], v[4:5], 0, v[142:143]
	v_lshl_add_u64 v[0:1], v[144:145], 0, v[130:131]
	v_mov_b32_e32 v133, v173
	v_or_b32_e32 v166, 3, v165
	global_load_dwordx4 v[36:39], v[4:5], off
	global_load_dwordx4 v[40:43], v[0:1], off offset:-96
	v_lshl_add_u64 v[0:1], v[140:141], 0, v[132:133]
	global_load_dword v131, v[0:1], off offset:-192
	v_min_u32_e32 v0, 4, v166
	v_lshl_add_u32 v6, v0, 6, v201
	v_add_u32_e32 v0, v6, v122
	v_max_i32_e32 v172, 0, v0
	v_lshl_add_u64 v[0:1], v[134:135], 0, v[172:173]
	v_lshlrev_b64 v[0:1], 11, v[0:1]
	v_lshl_add_u64 v[0:1], s[70:71], 0, v[0:1]
	v_add_u32_e32 v4, v6, v126
	v_lshl_add_u64 v[0:1], v[0:1], 0, v[2:3]
	v_max_i32_e32 v4, 0, v4
	v_lshl_add_u64 v[0:1], v[0:1], 0, v[142:143]
	v_lshlrev_b32_e32 v172, 1, v4
	v_lshl_add_u64 v[4:5], v[144:145], 0, v[172:173]
	global_load_dwordx4 v[44:47], v[0:1], off
	global_load_dwordx4 v[48:51], v[4:5], off
	v_add_u32_e32 v0, v6, v154
	v_max_i32_e32 v0, 0, v0
	v_lshlrev_b32_e32 v172, 2, v0
	v_lshl_add_u64 v[0:1], v[140:141], 0, v[172:173]
	global_load_dword v167, v[0:1], off
	v_min_u32_e32 v0, 5, v166
	v_lshl_add_u32 v6, v0, 6, v201
	v_add_u32_e32 v0, v6, v122
	v_max_i32_e32 v172, 0, v0
	v_lshl_add_u64 v[0:1], v[134:135], 0, v[172:173]
	v_lshlrev_b64 v[0:1], 11, v[0:1]
	v_lshl_add_u64 v[0:1], s[70:71], 0, v[0:1]
	v_add_u32_e32 v4, v6, v126
	v_lshl_add_u64 v[0:1], v[0:1], 0, v[2:3]
	v_max_i32_e32 v4, 0, v4
	v_lshl_add_u64 v[0:1], v[0:1], 0, v[142:143]
	v_lshlrev_b32_e32 v172, 1, v4
	v_lshl_add_u64 v[4:5], v[144:145], 0, v[172:173]
	global_load_dwordx4 v[52:55], v[0:1], off
	global_load_dwordx4 v[56:59], v[4:5], off
	v_add_u32_e32 v0, v6, v154
	v_max_i32_e32 v0, 0, v0
	v_lshlrev_b32_e32 v172, 2, v0
	v_lshl_add_u64 v[0:1], v[140:141], 0, v[172:173]
	global_load_dword v169, v[0:1], off
	v_sub_u32_e32 v0, 0, v8
	v_or_b32_e32 v1, v10, v155
	v_lshl_add_u64 v[146:147], v[128:129], 0, v[2:3]
	v_lshlrev_b32_e32 v0, 8, v0
	v_mov_b32_e32 v2, v173
	v_mov_b32_e32 v3, v173
	v_add_u32_e32 v133, s85, v1
	v_sub_u32_e32 v168, 0, v0
	v_mov_b32_e32 v172, v173
	v_mov_b32_e32 v0, v173
	v_mov_b32_e32 v1, v173
	v_mov_b64_e32 v[6:7], v[2:3]
	v_mov_b64_e32 v[10:11], v[2:3]
	v_mov_b64_e32 v[14:15], v[2:3]
	v_mov_b64_e32 v[18:19], v[2:3]
	v_mov_b64_e32 v[62:63], v[2:3]
	v_mov_b64_e32 v[66:67], v[2:3]
	v_mov_b64_e32 v[70:71], v[2:3]
	s_mov_b32 s60, s87
	s_mov_b32 s84, 0
	v_or_b32_e32 v143, 16, v133
	v_mov_b32_e32 v148, 0xff800000
	s_mov_b64 s[34:35], 0
	v_and_b32_e32 v170, 1, v235
	s_mov_b32 s87, 0
	v_mov_b64_e32 v[4:5], v[0:1]
	v_mov_b64_e32 v[8:9], v[0:1]
	v_mov_b64_e32 v[12:13], v[0:1]
	v_mov_b64_e32 v[16:17], v[0:1]
	v_mov_b64_e32 v[60:61], v[0:1]
	v_mov_b64_e32 v[64:65], v[0:1]
	v_mov_b64_e32 v[68:69], v[0:1]
	v_mov_b64_e32 v[136:137], v[172:173]
	v_mov_b32_e32 v149, 0xff800000
	v_min_u32_e32 v228, 6, v166
	v_lshl_add_u32 v234, v228, 6, v201
	v_add_u32_e32 v228, v234, v122
	v_add_u32_e32 v230, v234, v126
	v_max_i32_e32 v172, 0, v228
	v_max_i32_e32 v230, 0, v230
	v_lshl_add_u64 v[228:229], v[134:135], 0, v[172:173]
	v_lshlrev_b32_e32 v172, 1, v230
	v_add_u32_e32 v234, v234, v154
	v_lshlrev_b64 v[228:229], 11, v[228:229]
	v_lshl_add_u64 v[230:231], v[144:145], 0, v[172:173]
	v_max_i32_e32 v172, 0, v234
	v_lshl_add_u64 v[228:229], v[146:147], 0, v[228:229]
	v_lshl_add_u64 v[232:233], v[172:173], 2, v[140:141]
	v_mov_b32_e32 v172, v173
	s_branch .LBB0_798
